# N6 + non-producing wave requests its first two transpose-read groups before the rescale-flag wait; K prefetch behind them
# speedup vs baseline: 1.0181x; 1.0008x over previous
; #define SBAR() __builtin_amdgcn_sched_barrier(0)
; __device__ __forceinline__ int crow(int r, int hi) { return (r & 3) + 8 * (r >> 2) + 4 * hi; }
; #define KLOAD(k0) do { ks0 = *reinterpret_cast<const bf16x8*>(&Kh[(long)((k0) + sr) * LDK + sc]); ks1 = *reinterpret_cast<const bf16x8*>(&Kh[(long)((k0) + 32 + sr) * LDK + sc]); } while (0)
; template <int LDQ, int LDK, int LDO>
; __device__ __forceinline__ void attn_pair_body(const bf16* __restrict__ Qb, const bf16* __restrict__ Kh, const bf16* __restrict__ Vh, float* __restrict__ Ob, int NT, char* lds, int tid_in) {
;     ...
;     const float alp_v = ALp[pb * 32 + r32], m_v = Mp[r32];
;     const bf16x8 a0 = *reinterpret_cast<const bf16x8*>(Pp + pb * 4096 + 0 * 1024 + lane * 16), a1 = *reinterpret_cast<const bf16x8*>(Pp + pb * 4096 + 1 * 1024 + lane * 16);
;     const bf16x8 a2 = *reinterpret_cast<const bf16x8*>(Pp + pb * 4096 + 2 * 1024 + lane * 16), a3 = *reinterpret_cast<const bf16x8*>(Pp + pb * 4096 + 3 * 1024 + lane * 16);
;     SBAR();
;     KWRITE(b);
;     VWRITE(b);
;     { const int tk = j + 3 < NT ? j + 3 : NT - 1, tv = j + 1 < NT ? j + 1 : NT - 1; KLOAD(tk * KVBLK); VLOAD(tv * KVBLK); }
;     SBAR();
;     if (prod) {
;       if (flp) l_reg *= alp_v;
;       if (j >= 1) m_reg = m_v;
;       float mn, al; bf16x8 pa0, pa1, pa2, pa3;
;       partialSM(p0, p1, m_reg, mn, al);
;       finishSM(p0, p1, al, l_reg, pa0, pa1, pa2, pa3);
;       *reinterpret_cast<bf16x8*>(Pp + b * 4096 + 0 * 1024 + lane * 16) = pa0; *reinterpret_cast<bf16x8*>(Pp + b * 4096 + 1 * 1024 + lane * 16) = pa1;
;       *reinterpret_cast<bf16x8*>(Pp + b * 4096 + 2 * 1024 + lane * 16) = pa2; *reinterpret_cast<bf16x8*>(Pp + b * 4096 + 3 * 1024 + lane * 16) = pa3;
;       if (hi == 0) { ALp[b * 32 + r32] = al; Mp[r32] = m_reg; }
;       const unsigned fl = __any(al < 1.f) ? 1u : 0u;
;       if (lane == 0) FLp[b] = fl;
;       SBAR();
;     }
;     if (j >= 1) {
;       if (flp) {
; #pragma unroll
;         for (int d = 0; d < 4; ++d)
; #pragma unroll
;           for (int r = 0; r < 16; ++r) o[d][r] *= ALp[pb * 32 + crow(r, hi)];
;       }
;       pv_batched(o, vb0 + pb * 32768, a0, a1, a2, a3);
;     }
;     if (!prod && j + 1 < NT) { SBAR(); qkt_batched(p0, p1, (const bf16*)(K_lds + pb * 16384), qr, r32, hi); SBAR(); }
.Lpa_cons:
	v_lshl_add_u32 v157, s21, 12, v216
	ds_read_b128 v[168:171], v157
	ds_read_b128 v[164:167], v157 offset:1024
	ds_read_b128 v[160:163], v157 offset:2048
	ds_read_b128 v[156:159], v157 offset:3072
	v_lshl_add_u32 v219, s21, 15, v211
	ds_read_b64_tr_b16 v[220:221], v219 offset:0
	ds_read_b64_tr_b16 v[222:223], v219 offset:0x800
	ds_read_b64_tr_b16 v[224:225], v219 offset:0x1000
	ds_read_b64_tr_b16 v[226:227], v219 offset:0x1800
	ds_read_b64_tr_b16 v[234:235], v219 offset:0x2000
	ds_read_b64_tr_b16 v[236:237], v219 offset:0x2800
	ds_read_b64_tr_b16 v[238:239], v219 offset:0x3000
	ds_read_b64_tr_b16 v[240:241], v219 offset:0x3800
	ds_read_b64_tr_b16 v[242:243], v219 offset:0x200
	ds_read_b64_tr_b16 v[244:245], v219 offset:0xa00
	ds_read_b64_tr_b16 v[246:247], v219 offset:0x1200
	ds_read_b64_tr_b16 v[248:249], v219 offset:0x1a00
	ds_read_b64_tr_b16 v[176:177], v219 offset:0x2200
	ds_read_b64_tr_b16 v[178:179], v219 offset:0x2a00
	ds_read_b64_tr_b16 v[228:229], v219 offset:0x3200
	ds_read_b64_tr_b16 v[230:231], v219 offset:0x3a00
	s_waitcnt lgkmcnt(15)
	v_readfirstlane_b32 s29, v210
	s_cmp_lg_u32 s29, 0
	s_cselect_b64 s[62:63], -1, 0
	s_and_b64 s[62:63], s[62:63], s[56:57]
	s_andn2_b64 vcc, exec, s[56:57]
	s_cbranch_vccnz .Lpa_cons_j0
	s_lshl_b32 s28, s21, 5
	s_andn2_b64 vcc, exec, s[62:63]
	s_cbranch_vccnz .Lpa_cons_pv
	v_lshl_add_u32 v148, s28, 2, v215
	ds_read_b128 v[132:135], v148 offset:96
	ds_read_b128 v[136:139], v148 offset:64
	ds_read_b128 v[140:143], v148 offset:32
	ds_read_b128 v[144:147], v148
	s_waitcnt lgkmcnt(3)
	v_pk_mul_f32 v[18:19], v[18:19], v[134:135]
	s_waitcnt lgkmcnt(2)
	v_pk_mul_f32 v[14:15], v[14:15], v[138:139]
	s_waitcnt lgkmcnt(1)
	v_pk_mul_f32 v[10:11], v[10:11], v[142:143]
	s_waitcnt lgkmcnt(0)
	v_pk_mul_f32 v[6:7], v[6:7], v[146:147]
	v_pk_mul_f32 v[16:17], v[16:17], v[132:133]
	v_pk_mul_f32 v[12:13], v[12:13], v[136:137]
	v_pk_mul_f32 v[8:9], v[8:9], v[140:141]
	v_pk_mul_f32 v[4:5], v[4:5], v[144:145]
	v_pk_mul_f32 v[66:67], v[66:67], v[134:135]
	v_pk_mul_f32 v[62:63], v[62:63], v[138:139]
	v_pk_mul_f32 v[58:59], v[58:59], v[142:143]
	v_pk_mul_f32 v[54:55], v[54:55], v[146:147]
	v_pk_mul_f32 v[64:65], v[64:65], v[132:133]
	v_pk_mul_f32 v[60:61], v[60:61], v[136:137]
	v_pk_mul_f32 v[56:57], v[56:57], v[140:141]
	v_pk_mul_f32 v[52:53], v[52:53], v[144:145]
	v_pk_mul_f32 v[50:51], v[50:51], v[134:135]
	v_pk_mul_f32 v[46:47], v[46:47], v[138:139]
	v_pk_mul_f32 v[42:43], v[42:43], v[142:143]
	v_pk_mul_f32 v[38:39], v[38:39], v[146:147]
	v_pk_mul_f32 v[48:49], v[48:49], v[132:133]
	v_pk_mul_f32 v[44:45], v[44:45], v[136:137]
	v_pk_mul_f32 v[40:41], v[40:41], v[140:141]
	v_pk_mul_f32 v[36:37], v[36:37], v[144:145]
	v_pk_mul_f32 v[34:35], v[34:35], v[134:135]
	v_pk_mul_f32 v[30:31], v[30:31], v[138:139]
	v_pk_mul_f32 v[26:27], v[26:27], v[142:143]
	v_pk_mul_f32 v[22:23], v[22:23], v[146:147]
	v_pk_mul_f32 v[32:33], v[32:33], v[132:133]
	v_pk_mul_f32 v[28:29], v[28:29], v[136:137]
	v_pk_mul_f32 v[24:25], v[24:25], v[140:141]
	v_pk_mul_f32 v[20:21], v[20:21], v[144:145]
; #define SBAR() __builtin_amdgcn_sched_barrier(0)
; #define KRD(kb, D) do { _Pragma("unroll") for (int d = 0; d < 2; ++d) { const int cb = (((D) + d) * 16 + hi * 8) * 2; \
;     kb[2 * d] = *reinterpret_cast<const bf16x8*>((const char*)Ks + KSWZ(r32, cb)); kb[2 * d + 1] = *reinterpret_cast<const bf16x8*>((const char*)Ks + KSWZ(32 + r32, cb)); } } while (0)
; #define TRD(Lb, Hb, D0) Lb[0] = tr_read<v_rd_off(D0, 0, 0)>(vb); Hb[0] = tr_read<v_rd_off(D0, 0, 1)>(vb); Lb[1] = tr_read<v_rd_off(D0, 1, 0)>(vb); Hb[1] = tr_read<v_rd_off(D0, 1, 1)>(vb); \
;     Lb[2] = tr_read<v_rd_off(D0, 2, 0)>(vb); Hb[2] = tr_read<v_rd_off(D0, 2, 1)>(vb); Lb[3] = tr_read<v_rd_off(D0, 3, 0)>(vb); Hb[3] = tr_read<v_rd_off(D0, 3, 1)>(vb);
; #define MM(D0, Lb, Hb) o[D0] = __builtin_amdgcn_mfma_f32_32x32x16_bf16(pa0, PK(Lb[0], Hb[0]), o[D0], 0, 0, 0); o[D0] = __builtin_amdgcn_mfma_f32_32x32x16_bf16(pa1, PK(Lb[1], Hb[1]), o[D0], 0, 0, 0); \
;     o[D0] = __builtin_amdgcn_mfma_f32_32x32x16_bf16(pa2, PK(Lb[2], Hb[2]), o[D0], 0, 0, 0); o[D0] = __builtin_amdgcn_mfma_f32_32x32x16_bf16(pa3, PK(Lb[3], Hb[3]), o[D0], 0, 0, 0);
; __device__ __forceinline__ void qkt_batched(f32x16& p0, f32x16& p1, const bf16* Ks, const bf16x8* qr, int r32, int hi) {
;   p0 = f32x16{}; p1 = f32x16{};
;   bf16x8 k0[4], k1[4], k2[4];
;     ...
;   KRD(k0, 0); SBAR(); KRD(k1, 2); SBAR();
; __device__ __forceinline__ void pv_batched(f32x16* o, int vb, bf16x8 pa0, bf16x8 pa1, bf16x8 pa2, bf16x8 pa3) {
;   s16x4 L0[4], H0[4], L1[4], H1[4];
;     ...
;   TRD(L0, H0, 0) SBAR(); TRD(L1, H1, 1) SBAR();
;   asm volatile("s_waitcnt lgkmcnt(8)" ::: "memory"); SBAR();
;   MM(0, L0, H0) SBAR();
;   TRD(L0, H0, 2) SBAR();
;   asm volatile("s_waitcnt lgkmcnt(8)" ::: "memory"); SBAR();
;   MM(1, L1, H1) SBAR();
;   TRD(L1, H1, 3) SBAR();
;   asm volatile("s_waitcnt lgkmcnt(8)" ::: "memory"); SBAR();
;   MM(2, L0, H0) SBAR();
;   asm volatile("s_waitcnt lgkmcnt(0)" ::: "memory"); SBAR();
;   MM(3, L1, H1) SBAR();
;     ...
; }
.Lpa_cons_pv:
	s_lshl_b32 s94, s21, 14
	s_add_i32 s94, s94, 0x10000
	v_add3_u32 v139, s94, v194, v192
	v_add3_u32 v147, s94, v193, v192
	v_add3_u32 v155, s94, v195, v192
	ds_read_b128 v[132:135], v139
	ds_read_b128 v[136:139], v139 offset:8192
	ds_read_b128 v[140:143], v147
	ds_read_b128 v[144:147], v147 offset:8192
	ds_read_b128 v[148:151], v155
	ds_read_b128 v[152:155], v155 offset:8192
	s_xor_b32 s65, s65, 0x4000
	s_xor_b32 s77, s77, 0x8000
	s_add_u32 s74, s74, 0x90000
	s_addc_u32 s75, s75, 0
	s_add_u32 s92, s92, 0x90000
	s_addc_u32 s93, s93, 0
	s_add_u32 s96, s96, 0x90000
	s_addc_u32 s97, s97, 0
	s_mov_b32 m0, s65
	s_waitcnt lgkmcnt(14)
	s_nop 0
	v_mfma_f32_32x32x16_bf16 v[4:19], v[168:171], v[220:223], v[4:19]
	global_load_lds_dwordx4 v172, s[74:75]
	s_add_i32 m0, s65, 0x400
	v_mfma_f32_32x32x16_bf16 v[4:19], v[164:167], v[224:227], v[4:19]
	v_mfma_f32_32x32x16_bf16 v[4:19], v[160:163], v[234:237], v[4:19]
	global_load_lds_dwordx4 v173, s[74:75]
	s_mov_b32 m0, s77
	v_mfma_f32_32x32x16_bf16 v[4:19], v[156:159], v[238:241], v[4:19]
	ds_read_b64_tr_b16 v[220:221], v219 offset:0x400
	ds_read_b64_tr_b16 v[222:223], v219 offset:0xc00
	ds_read_b64_tr_b16 v[224:225], v219 offset:0x1400
	ds_read_b64_tr_b16 v[226:227], v219 offset:0x1c00
	ds_read_b64_tr_b16 v[232:233], v219 offset:0x2400
	ds_read_b64_tr_b16 v[234:235], v219 offset:0x2c00
	ds_read_b64_tr_b16 v[236:237], v219 offset:0x3400
	ds_read_b64_tr_b16 v[238:239], v219 offset:0x3c00
	s_waitcnt lgkmcnt(8)
	v_mfma_f32_32x32x16_bf16 v[52:67], v[168:171], v[242:245], v[52:67]
	global_load_lds_dwordx4 v174, s[92:93]
	s_add_i32 m0, s77, 0x380
	v_mfma_f32_32x32x16_bf16 v[52:67], v[164:167], v[246:249], v[52:67]
	v_mfma_f32_32x32x16_bf16 v[52:67], v[160:163], v[176:179], v[52:67]
	global_load_lds_dwordx4 v174, s[92:93] offset:128
	s_add_i32 m0, s77, 0x800
	v_mfma_f32_32x32x16_bf16 v[52:67], v[156:159], v[228:231], v[52:67]
	ds_read_b64_tr_b16 v[176:177], v219 offset:0x600
	ds_read_b64_tr_b16 v[178:179], v219 offset:0xe00
	ds_read_b64_tr_b16 v[228:229], v219 offset:0x1600
	ds_read_b64_tr_b16 v[230:231], v219 offset:0x1e00
	ds_read_b64_tr_b16 v[240:241], v219 offset:0x2600
	ds_read_b64_tr_b16 v[242:243], v219 offset:0x2e00
	ds_read_b64_tr_b16 v[244:245], v219 offset:0x3600
	ds_read_b64_tr_b16 v[246:247], v219 offset:0x3e00
	s_waitcnt lgkmcnt(8)
	v_mfma_f32_32x32x16_bf16 v[36:51], v[168:171], v[220:223], v[36:51]
	global_load_lds_dwordx4 v174, s[96:97]
	s_add_i32 m0, s77, 0xb80
	v_mfma_f32_32x32x16_bf16 v[36:51], v[164:167], v[224:227], v[36:51]
	v_mfma_f32_32x32x16_bf16 v[36:51], v[160:163], v[232:235], v[36:51]
	global_load_lds_dwordx4 v174, s[96:97] offset:128
	v_mfma_f32_32x32x16_bf16 v[36:51], v[156:159], v[236:239], v[36:51]
	s_waitcnt lgkmcnt(0)
	v_mfma_f32_32x32x16_bf16 v[20:35], v[168:171], v[176:179], v[20:35]
	v_mfma_f32_32x32x16_bf16 v[20:35], v[164:167], v[228:231], v[20:35]
	v_mfma_f32_32x32x16_bf16 v[20:35], v[160:163], v[240:243], v[20:35]
	v_mfma_f32_32x32x16_bf16 v[20:35], v[156:159], v[244:247], v[20:35]
	s_branch .LBB0_1034
.Lpa_cons_j0:
	s_lshl_b32 s94, s21, 14
	s_add_i32 s94, s94, 0x10000
	v_add3_u32 v139, s94, v194, v192
	v_add3_u32 v147, s94, v193, v192
	v_add3_u32 v155, s94, v195, v192
	ds_read_b128 v[132:135], v139
	ds_read_b128 v[136:139], v139 offset:8192
	ds_read_b128 v[140:143], v147
	ds_read_b128 v[144:147], v147 offset:8192
	ds_read_b128 v[148:151], v155
	ds_read_b128 v[152:155], v155 offset:8192
	s_xor_b32 s65, s65, 0x4000
	s_xor_b32 s77, s77, 0x8000
	s_add_u32 s74, s74, 0x90000
	s_addc_u32 s75, s75, 0
	s_add_u32 s92, s92, 0x90000
	s_addc_u32 s93, s93, 0
	s_add_u32 s96, s96, 0x90000
	s_addc_u32 s97, s97, 0
	s_mov_b32 m0, s65
	s_nop 0
	global_load_lds_dwordx4 v172, s[74:75]
	s_add_i32 m0, s65, 0x400
	s_nop 0
	global_load_lds_dwordx4 v173, s[74:75]
	s_mov_b32 m0, s77
	s_nop 0
	global_load_lds_dwordx4 v174, s[92:93]
	s_add_i32 m0, s77, 0x380
	s_nop 0
	global_load_lds_dwordx4 v174, s[92:93] offset:128
	s_add_i32 m0, s77, 0x800
	s_nop 0
	global_load_lds_dwordx4 v174, s[96:97]
	s_add_i32 m0, s77, 0xb80
	s_nop 0
	global_load_lds_dwordx4 v174, s[96:97] offset:128
	s_branch .LBB0_1034
